# attnA: one static s_setprio 1 for waves 4-7 around the tile loop (lowered again at loop exit)
# baseline (speedup 1.0000x reference)
.LBB0_484:
	s_lshl_b32 s3, s5, 7
	s_and_b32 s23, s3, 0x380
	v_ashrrev_i32_e32 v207, 31, v206
	s_ashr_i32 s5, s4, 31
	s_add_i32 s24, s23, s11
	v_lshlrev_b64 v[4:5], 12, v[206:207]
	s_lshl_b64 s[4:5], s[4:5], 10
	v_lshl_add_u64 v[4:5], s[80:81], 0, v[4:5]
	s_ashr_i32 s25, s24, 31
	s_or_b32 s3, s4, s23
	v_lshl_add_u64 v[4:5], s[24:25], 1, v[4:5]
	v_lshlrev_b32_e32 v184, 1, v192
	s_mul_i32 s24, s3, 0x2200
	s_mul_hi_u32 s3, s3, 0x2200
	s_mul_i32 s4, s5, 0x2200
	s_or_b32 s17, s10, 4
	v_lshl_add_u64 v[4:5], v[4:5], 0, v[184:185]
	s_add_i32 s3, s3, s4
	s_lshl_b32 s4, s23, 1
	global_load_dwordx4 v[160:163], v[4:5], off
	global_load_dwordx4 v[156:159], v[4:5], off offset:32
	global_load_dwordx4 v[152:155], v[4:5], off offset:64
	global_load_dwordx4 v[148:151], v[4:5], off offset:96
	s_add_u32 s4, s28, s4
	v_add_u32_e32 v4, v2, v217
	s_addc_u32 s5, s29, 0
	v_readlane_b32 s36, v241, 45
	v_ashrrev_i32_e32 v5, 31, v4
	v_add_u32_e32 v2, v2, v218
	v_readlane_b32 s37, v241, 46
	s_add_u32 s24, s36, s24
	v_lshlrev_b64 v[4:5], 12, v[4:5]
	v_ashrrev_i32_e32 v3, 31, v2
	s_addc_u32 s25, s37, s3
	v_lshl_add_u64 v[4:5], s[4:5], 0, v[4:5]
	v_lshlrev_b64 v[2:3], 12, v[2:3]
	s_lshl_b32 s3, s26, 1
	v_lshl_add_u64 v[4:5], v[4:5], 0, v[200:201]
	v_lshl_add_u64 v[2:3], s[4:5], 0, v[2:3]
	s_add_u32 s26, s24, s3
	global_load_dwordx4 v[4:7], v[4:5], off
	v_lshl_add_u64 v[2:3], v[2:3], 0, v[202:203]
	s_addc_u32 s27, s25, 0
	v_mov_b32_e32 v205, v185
	global_load_dwordx4 v[8:11], v[2:3], off
	v_lshl_add_u64 v[2:3], s[26:27], 0, v[204:205]
	v_lshl_add_u64 v[12:13], v[2:3], 0, v[196:197]
	global_load_dwordx4 v[12:15], v[12:13], off
	v_lshl_add_u64 v[2:3], v[2:3], 0, v[198:199]
	global_load_dwordx4 v[16:19], v[2:3], off
	s_or_b32 s3, s16, 64
	s_add_i32 s34, s31, 0x4040
	s_and_b64 s[26:27], s[6:7], exec
	s_cselect_b32 s3, s3, s34
	v_add_u32_e32 v2, s3, v217
	v_ashrrev_i32_e32 v3, 31, v2
	v_add_u32_e32 v20, v193, v231
	v_lshlrev_b64 v[2:3], 12, v[2:3]
	v_add_u32_e32 v237, 0x8800, v20
	v_lshl_add_u64 v[2:3], s[4:5], 0, v[2:3]
	v_lshl_add_u64 v[2:3], v[2:3], 0, v[200:201]
	v_add_u32_e32 v21, v193, v232
	v_add_u32_e32 v236, 0x8800, v21
	v_lshl_add_u64 v[208:209], s[24:25], 0, v[204:205]
	v_readlane_b32 s36, v242, 63
	v_readlane_b32 s37, v241, 0
	v_readlane_b32 s38, v241, 1
	v_readlane_b32 s39, v241, 2
	v_readlane_b32 s40, v241, 3
	v_readlane_b32 s41, v241, 4
	v_readlane_b32 s42, v241, 5
	v_readlane_b32 s43, v241, 6
	v_readlane_b32 s44, v241, 7
	v_readlane_b32 s45, v241, 8
	v_readlane_b32 s46, v241, 9
	v_readlane_b32 s47, v241, 10
	v_readlane_b32 s48, v241, 11
	v_readlane_b32 s49, v241, 12
	v_readlane_b32 s50, v241, 13
	v_readlane_b32 s51, v241, 14
	v_mov_b64_e32 v[34:35], s[36:37]
	v_mov_b64_e32 v[36:37], s[38:39]
	v_mov_b64_e32 v[38:39], s[40:41]
	v_mov_b64_e32 v[40:41], s[42:43]
	v_mov_b64_e32 v[42:43], s[44:45]
	v_mov_b64_e32 v[44:45], s[46:47]
	v_mov_b64_e32 v[46:47], s[48:49]
	v_mov_b64_e32 v[48:49], s[50:51]
	v_mov_b64_e32 v[100:101], s[70:71]
	v_mov_b64_e32 v[98:99], s[68:69]
	v_lshl_add_u64 v[210:211], s[4:5], 0, v[200:201]
	v_lshl_add_u64 v[212:213], s[4:5], 0, v[202:203]
	v_readlane_b32 s48, v241, 29
	s_waitcnt vmcnt(3)
	ds_write_b128 v234, v[4:7]
	s_waitcnt vmcnt(2)
	ds_write_b128 v235, v[8:11]
	v_add_u32_e32 v6, s3, v218
	s_lshl_b32 s3, s22, 1
	v_ashrrev_i32_e32 v7, 31, v6
	s_add_u32 s26, s24, s3
	v_lshlrev_b64 v[6:7], 12, v[6:7]
	s_addc_u32 s27, s25, 0
	s_waitcnt vmcnt(1)
	ds_write2_b64 v237, v[12:13], v[14:15] offset1:2
	v_lshl_add_u64 v[6:7], s[4:5], 0, v[6:7]
	v_lshl_add_u64 v[14:15], s[26:27], 0, v[204:205]
	global_load_dwordx4 v[2:5], v[2:3], off
	v_lshl_add_u64 v[6:7], v[6:7], 0, v[202:203]
	v_lshl_add_u64 v[10:11], v[14:15], 0, v[196:197]
	global_load_dwordx4 v[6:9], v[6:7], off
	v_lshl_add_u64 v[14:15], v[14:15], 0, v[198:199]
	global_load_dwordx4 v[10:13], v[10:11], off
	s_waitcnt vmcnt(3)
	ds_write2_b64 v236, v[16:17], v[18:19] offset1:2
	global_load_dwordx4 v[14:17], v[14:15], off
	s_add_i32 s22, s31, 0x3000
	s_sub_i32 s3, 0x42, s10
	s_and_b64 s[6:7], s[6:7], exec
	s_cselect_b32 s3, 2, s3
	s_lshl_b32 s7, s3, 6
	s_or_b32 s6, s16, 0x80
	s_add_i32 s24, s22, s7
	s_waitcnt lgkmcnt(0)
	s_barrier
	s_cmp_lt_u32 s3, 64
	s_cselect_b32 s6, s6, s24
	s_cselect_b32 s3, 0x80, s7
	s_lshl_b32 s78, s3, 1
	s_waitcnt vmcnt(3)
	ds_write_b128 v234, v[2:5] offset:17408
	s_waitcnt vmcnt(2)
	ds_write_b128 v235, v[6:9] offset:17408
	v_add_u32_e32 v2, 0xd000, v20
	s_waitcnt vmcnt(1)
	ds_write2_b64 v2, v[10:11], v[12:13] offset1:2
	v_add_u32_e32 v2, 0xd000, v21
	s_waitcnt vmcnt(0)
	ds_write2_b64 v2, v[14:15], v[16:17] offset1:2
	v_add_u32_e32 v2, s6, v217
	v_ashrrev_i32_e32 v3, 31, v2
	v_lshlrev_b64 v[2:3], 12, v[2:3]
	v_lshl_add_u64 v[2:3], s[4:5], 0, v[2:3]
	v_lshl_add_u64 v[2:3], v[2:3], 0, v[200:201]
	global_load_dwordx4 v[164:167], v[2:3], off
	v_add_u32_e32 v2, s6, v218
	v_ashrrev_i32_e32 v3, 31, v2
	v_lshlrev_b64 v[2:3], 12, v[2:3]
	v_lshl_add_u64 v[2:3], s[4:5], 0, v[2:3]
	v_lshl_add_u64 v[2:3], v[2:3], 0, v[202:203]
	global_load_dwordx4 v[168:171], v[2:3], off
	v_lshl_add_u64 v[2:3], v[208:209], 0, s[78:79]
	v_lshl_add_u64 v[4:5], v[2:3], 0, v[196:197]
	v_lshl_add_u64 v[2:3], v[2:3], 0, v[198:199]
	global_load_dwordx4 v[176:179], v[4:5], off
	global_load_dwordx4 v[172:175], v[2:3], off
	ds_read_b128 v[50:53], v214 offset:8704
	ds_read_b128 v[18:21], v214
	ds_read_b128 v[54:57], v214 offset:32
	s_waitcnt lgkmcnt(1)
	v_mfma_f32_32x32x16_bf16 v[2:17], v[18:21], v[160:163], v[34:49]
	s_mov_b32 s5, 0
	s_sub_i32 s6, 0, s10
	v_mfma_f32_32x32x16_bf16 v[18:33], v[50:53], v[160:163], v[34:49]
	s_nop 6
	ds_read_b128 v[34:37], v214 offset:8736
	s_waitcnt lgkmcnt(1)
	v_mfma_f32_32x32x16_bf16 v[2:17], v[54:57], v[156:159], v[2:17]
	s_waitcnt lgkmcnt(0)
	v_mfma_f32_32x32x16_bf16 v[18:33], v[34:37], v[156:159], v[18:33]
	ds_read_b128 v[34:37], v214 offset:64
	ds_read_b128 v[38:41], v214 offset:8768
	s_waitcnt lgkmcnt(1)
	v_mfma_f32_32x32x16_bf16 v[2:17], v[34:37], v[152:155], v[2:17]
	s_waitcnt lgkmcnt(0)
	v_mfma_f32_32x32x16_bf16 v[18:33], v[38:41], v[152:155], v[18:33]
	ds_read_b128 v[34:37], v214 offset:96
	ds_read_b128 v[38:41], v214 offset:8800
	s_waitcnt lgkmcnt(1)
	v_mfma_f32_32x32x16_bf16 v[2:17], v[34:37], v[148:151], v[2:17]
	s_waitcnt lgkmcnt(0)
	v_mfma_f32_32x32x16_bf16 v[18:33], v[38:41], v[148:151], v[18:33]
	s_nop 9
	v_max_f32_e32 v34, v3, v3
	v_max_f32_e32 v35, v2, v2
	v_max_f32_e32 v34, v35, v34
	v_max3_f32 v35, v5, v6, v7
	v_max3_f32 v34, v34, v4, v8
	v_max3_f32 v35, v35, v10, v11
	v_max3_f32 v34, v34, v9, v12
	v_max3_f32 v36, v18, v19, v20
	v_max3_f32 v37, v21, v22, v23
	v_max3_f32 v36, v36, v24, v25
	v_max3_f32 v37, v37, v26, v27
	v_max3_f32 v35, v35, v14, v15
	v_max3_f32 v36, v36, v28, v29
	v_max3_f32 v34, v34, v13, v16
	v_max3_f32 v37, v37, v30, v31
	v_max3_f32 v36, v36, v32, v33
	v_max3_f32 v34, v34, v17, v35
	v_max3_f32 v34, v34, v36, v37
	ds_bpermute_b32 v35, v67, v34
	s_waitcnt lgkmcnt(0)
	v_max_f32_e32 v35, v35, v35
	v_max_f32_e32 v205, v34, v35
	v_sub_f32_e32 v2, v2, v205
	v_sub_f32_e32 v3, v3, v205
	v_sub_f32_e32 v4, v4, v205
	v_sub_f32_e32 v5, v5, v205
	v_exp_f32_e32 v2, v2
	v_exp_f32_e32 v3, v3
	v_exp_f32_e32 v4, v4
	v_exp_f32_e32 v5, v5
	v_sub_f32_e32 v6, v6, v205
	v_sub_f32_e32 v7, v7, v205
	v_sub_f32_e32 v8, v8, v205
	v_sub_f32_e32 v9, v9, v205
	v_exp_f32_e32 v6, v6
	v_exp_f32_e32 v7, v7
	v_exp_f32_e32 v8, v8
	v_exp_f32_e32 v9, v9
	v_cvt_pk_bf16_f32 v68, v2, v3
	v_cvt_pk_bf16_f32 v69, v4, v5
	ds_read_b128 v[2:5], v215 offset:34816
	ds_read_b128 v[72:75], v215 offset:34848
	v_cvt_pk_bf16_f32 v70, v6, v7
	v_cvt_pk_bf16_f32 v71, v8, v9
	v_sub_f32_e32 v10, v10, v205
	v_sub_f32_e32 v11, v11, v205
	s_waitcnt lgkmcnt(1)
	v_mfma_f32_32x32x16_bf16 v[50:65], v[2:5], v[68:71], 0
	ds_read_b128 v[2:5], v215 offset:39424
	v_sub_f32_e32 v12, v12, v205
	v_sub_f32_e32 v13, v13, v205
	v_sub_f32_e32 v14, v14, v205
	v_sub_f32_e32 v15, v15, v205
	v_sub_f32_e32 v16, v16, v205
	v_sub_f32_e32 v17, v17, v205
	v_exp_f32_e32 v10, v10
	v_exp_f32_e32 v11, v11
	v_exp_f32_e32 v12, v12
	v_exp_f32_e32 v13, v13
	v_exp_f32_e32 v14, v14
	v_exp_f32_e32 v15, v15
	v_exp_f32_e32 v16, v16
	v_exp_f32_e32 v17, v17
	v_cvt_pk_bf16_f32 v94, v10, v11
	v_cvt_pk_bf16_f32 v95, v12, v13
	v_cvt_pk_bf16_f32 v96, v14, v15
	v_cvt_pk_bf16_f32 v97, v16, v17
	v_sub_f32_e32 v18, v18, v205
	v_sub_f32_e32 v19, v19, v205
	s_waitcnt lgkmcnt(1)
	v_mfma_f32_32x32x16_bf16 v[50:65], v[72:75], v[94:97], v[50:65]
	ds_read_b128 v[72:75], v215 offset:39456
	v_sub_f32_e32 v20, v20, v205
	v_sub_f32_e32 v21, v21, v205
	v_sub_f32_e32 v22, v22, v205
	v_sub_f32_e32 v23, v23, v205
	v_sub_f32_e32 v24, v24, v205
	v_sub_f32_e32 v25, v25, v205
	s_waitcnt lgkmcnt(1)
	v_mfma_f32_32x32x16_bf16 v[34:49], v[2:5], v[68:71], 0
	ds_read_b128 v[2:5], v215 offset:44032
	v_sub_f32_e32 v26, v26, v205
	v_sub_f32_e32 v27, v27, v205
	v_sub_f32_e32 v28, v28, v205
	v_sub_f32_e32 v29, v29, v205
	v_sub_f32_e32 v30, v30, v205
	v_sub_f32_e32 v31, v31, v205
	v_sub_f32_e32 v32, v32, v205
	v_sub_f32_e32 v33, v33, v205
	v_exp_f32_e32 v18, v18
	v_exp_f32_e32 v19, v19
	v_exp_f32_e32 v20, v20
	v_exp_f32_e32 v21, v21
	v_exp_f32_e32 v22, v22
	v_exp_f32_e32 v23, v23
	v_exp_f32_e32 v24, v24
	v_exp_f32_e32 v25, v25
	v_exp_f32_e32 v26, v26
	v_exp_f32_e32 v27, v27
	v_exp_f32_e32 v28, v28
	v_exp_f32_e32 v29, v29
	v_exp_f32_e32 v30, v30
	v_exp_f32_e32 v31, v31
	v_exp_f32_e32 v32, v32
	v_exp_f32_e32 v33, v33
	s_waitcnt lgkmcnt(1)
	v_mfma_f32_32x32x16_bf16 v[34:49], v[72:75], v[94:97], v[34:49]
	ds_read_b128 v[72:75], v215 offset:44064
	v_cvt_pk_bf16_f32 v90, v18, v19
	v_cvt_pk_bf16_f32 v91, v20, v21
	v_cvt_pk_bf16_f32 v92, v22, v23
	v_cvt_pk_bf16_f32 v93, v24, v25
	v_cvt_pk_bf16_f32 v86, v26, v27
	v_cvt_pk_bf16_f32 v87, v28, v29
	v_cvt_pk_bf16_f32 v88, v30, v31
	v_cvt_pk_bf16_f32 v89, v32, v33
	s_waitcnt lgkmcnt(1)
	v_mfma_f32_32x32x16_bf16 v[18:33], v[2:5], v[68:71], 0
	ds_read_b128 v[2:5], v215 offset:48640
	v_xor_b32_e32 v84, 0x80000000, v205
	v_mov_b32_e32 v85, v84
	s_waitcnt lgkmcnt(1)
	v_mfma_f32_32x32x16_bf16 v[18:33], v[72:75], v[94:97], v[18:33]
	ds_read_b128 v[72:75], v215 offset:48672
	s_waitcnt lgkmcnt(1)
	v_mfma_f32_32x32x16_bf16 v[2:17], v[2:5], v[68:71], 0
	s_waitcnt lgkmcnt(0)
	v_mfma_f32_32x32x16_bf16 v[2:17], v[72:75], v[94:97], v[2:17]
	ds_read_b128 v[72:75], v215 offset:34880
	s_waitcnt lgkmcnt(0)
	v_mfma_f32_32x32x16_bf16 v[50:65], v[72:75], v[90:93], v[50:65]
	ds_read_b128 v[72:75], v215 offset:39488
	s_waitcnt lgkmcnt(0)
	v_mfma_f32_32x32x16_bf16 v[34:49], v[72:75], v[90:93], v[34:49]
	ds_read_b128 v[72:75], v215 offset:44096
	s_waitcnt lgkmcnt(0)
	v_mfma_f32_32x32x16_bf16 v[18:33], v[72:75], v[90:93], v[18:33]
	ds_read_b128 v[72:75], v215 offset:48704
	s_waitcnt lgkmcnt(0)
	v_mfma_f32_32x32x16_bf16 v[2:17], v[72:75], v[90:93], v[2:17]
	ds_read_b128 v[72:75], v215 offset:34912
	s_waitcnt lgkmcnt(0)
	v_mfma_f32_32x32x16_bf16 v[50:65], v[72:75], v[86:89], v[50:65]
	ds_read_b128 v[72:75], v215 offset:39520
	s_waitcnt lgkmcnt(0)
	v_mfma_f32_32x32x16_bf16 v[34:49], v[72:75], v[86:89], v[34:49]
	ds_read_b128 v[72:75], v215 offset:44128
	s_waitcnt lgkmcnt(0)
	v_mfma_f32_32x32x16_bf16 v[18:33], v[72:75], v[86:89], v[18:33]
	ds_read_b128 v[72:75], v215 offset:48736
	s_waitcnt lgkmcnt(0)
	s_barrier
	v_mfma_f32_32x32x16_bf16 v[2:17], v[72:75], v[86:89], v[2:17]
	v_mfma_f32_32x32x16_bf16 v[68:83], v[98:101], v[68:71], 0
	v_mfma_f32_32x32x16_bf16 v[68:83], v[98:101], v[94:97], v[68:83]
	v_mov_b32_e32 v94, v84
	v_mov_b32_e32 v95, v84
	v_mov_b32_e32 v96, v84
	v_mov_b32_e32 v97, v84
	v_mfma_f32_32x32x16_bf16 v[68:83], v[98:101], v[90:93], v[68:83]
	v_mov_b32_e32 v90, v84
	v_mov_b32_e32 v91, v84
	v_mov_b32_e32 v92, v84
	v_mov_b32_e32 v93, v84
	v_mfma_f32_32x32x16_bf16 v[68:83], v[98:101], v[86:89], v[68:83]
	v_mov_b32_e32 v86, v84
	v_mov_b32_e32 v87, v84
	v_mov_b32_e32 v88, v84
	v_mov_b32_e32 v89, v84
	v_mov_b32_e32 v98, v84
	v_mov_b32_e32 v99, v84
	s_and_b64 vcc, exec, s[0:1]
	s_cbranch_vccz .Lattn_a_noprio
	s_setprio 1
.Lattn_a_noprio:
	s_cmp_lg_u32 s100, 0
	s_cbranch_scc1 .Lattn_af_loop

.Lattn_a_exit:
	s_setprio 0
	s_waitcnt vmcnt(0)
	v_mov_b64_e32 v[100:101], v[84:85]
	v_mov_b64_e32 v[102:103], v[86:87]
	v_mov_b64_e32 v[104:105], v[88:89]
	v_mov_b64_e32 v[106:107], v[90:91]
	v_mov_b64_e32 v[108:109], v[92:93]
	v_mov_b64_e32 v[110:111], v[94:95]
	v_mov_b64_e32 v[112:113], v[96:97]
	v_mov_b64_e32 v[114:115], v[98:99]
	s_branch .LBB0_491
